# speedup vs baseline: 1.0117x; 1.0117x over previous
; __device__ __forceinline__ float silu_(float x) { return x * rcp_(1.f + __expf(-x)); }
; template <int EPI>
; __device__ __forceinline__ void gemm_phase(const Params& p, const u16* __restrict__ A, const u16* __restrict__ Bt, int K, int nN,
;                            u16* __restrict__ Cout, int ldc) {
;     ...
; #pragma unroll
;       for (int m = 0; m < 8; ++m) {
; #pragma unroll
;         for (int j = 0; j < 4; ++j) {
;           const float rs = rsl[wr * 128 + m * 16 + fqe * 4 + j];
;           u16* d = stg + (wr * 128 + m * 16 + fqe * 4 + j) * 128 + (fre & 7);
; #pragma unroll
;           for (int n2 = 0; n2 < 2; ++n2) {
;             const float g = acc[m][2 * n2][j] * rs, u = acc[m][2 * n2 + 1][j] * rs;
;             const int chunk = (wc * 4 + n2 * 2 + (fre >> 3)) ^ fqe;
;             d[chunk * 8] = f2bf(silu_(g) * u);
;           }
;         }
;         __builtin_amdgcn_sched_barrier(0);
;       }
.LBB0_1126:
	v_lshl_add_u32 v222, v192, 2, v196
	v_lshl_add_u32 v223, v222, 2, v187
	ds_read_b128 v[128:131], v223 offset:0
	ds_read_b128 v[132:135], v223 offset:64
	ds_read_b128 v[136:139], v223 offset:128
	ds_read_b128 v[140:143], v223 offset:192
	ds_read_b128 v[144:147], v223 offset:256
	ds_read_b128 v[148:151], v223 offset:320
	ds_read_b128 v[152:155], v223 offset:384
	ds_read_b128 v[156:159], v223 offset:448
	v_and_b32_e32 v224, 7, v174
	v_lshrrev_b32_e32 v225, 3, v174
	v_add_u32_e32 v225, v225, v197
	v_lshlrev_b32_e32 v224, 1, v224
	v_lshl_or_b32 v224, v222, 8, v224
	v_xor_b32_e32 v226, v225, v192
	v_add_u32_e32 v227, 2, v225
	v_xor_b32_e32 v227, v227, v192
	v_lshl_add_u32 v160, v226, 4, v224
	v_lshl_add_u32 v161, v227, 4, v224
	v_add_u32_e32 v160, 0x10000, v160
	v_add_u32_e32 v161, 0x10000, v161
	s_waitcnt lgkmcnt(0)
	v_mul_f32_e32 v162, v124, v128
	v_mul_f32_e32 v163, v125, v129
	v_mul_f32_e32 v164, v126, v130
	v_mul_f32_e32 v165, v127, v131
	v_mul_f32_e32 v166, v116, v128
	v_mul_f32_e32 v167, v117, v129
	v_mul_f32_e32 v168, v118, v130
	v_mul_f32_e32 v169, v119, v131
	v_mul_f32_e32 v214, 0xbfb8aa3b, v162
	v_mul_f32_e32 v215, 0xbfb8aa3b, v163
	v_mul_f32_e32 v216, 0xbfb8aa3b, v164
	v_mul_f32_e32 v217, 0xbfb8aa3b, v165
	v_mul_f32_e32 v218, 0xbfb8aa3b, v166
	v_mul_f32_e32 v219, 0xbfb8aa3b, v167
	v_mul_f32_e32 v220, 0xbfb8aa3b, v168
	v_mul_f32_e32 v221, 0xbfb8aa3b, v169
	v_exp_f32_e32 v214, v214
	v_exp_f32_e32 v215, v215
	v_exp_f32_e32 v216, v216
	v_exp_f32_e32 v217, v217
	v_exp_f32_e32 v218, v218
	v_exp_f32_e32 v219, v219
	v_exp_f32_e32 v220, v220
	v_exp_f32_e32 v221, v221
	v_mul_f32_e32 v206, v120, v128
	v_mul_f32_e32 v207, v121, v129
	v_mul_f32_e32 v208, v122, v130
	v_mul_f32_e32 v209, v123, v131
	v_mul_f32_e32 v210, v112, v128
	v_mul_f32_e32 v211, v113, v129
	v_mul_f32_e32 v212, v114, v130
	v_mul_f32_e32 v213, v115, v131
	v_add_f32_e32 v214, 1.0, v214
	v_add_f32_e32 v215, 1.0, v215
	v_add_f32_e32 v216, 1.0, v216
	v_add_f32_e32 v217, 1.0, v217
	v_add_f32_e32 v218, 1.0, v218
	v_add_f32_e32 v219, 1.0, v219
	v_add_f32_e32 v220, 1.0, v220
	v_add_f32_e32 v221, 1.0, v221
	v_rcp_f32_e32 v214, v214
	v_rcp_f32_e32 v215, v215
	v_rcp_f32_e32 v216, v216
	v_rcp_f32_e32 v217, v217
	v_rcp_f32_e32 v218, v218
	v_rcp_f32_e32 v219, v219
	v_rcp_f32_e32 v220, v220
	v_rcp_f32_e32 v221, v221
	v_mul_f32_e32 v162, v162, v214
	v_mul_f32_e32 v163, v163, v215
	v_mul_f32_e32 v164, v164, v216
	v_mul_f32_e32 v165, v165, v217
	v_mul_f32_e32 v166, v166, v218
	v_mul_f32_e32 v167, v167, v219
	v_mul_f32_e32 v168, v168, v220
	v_mul_f32_e32 v169, v169, v221
	v_mul_f32_e32 v206, v206, v162
	v_mul_f32_e32 v207, v207, v163
	v_mul_f32_e32 v208, v208, v164
	v_mul_f32_e32 v209, v209, v165
	v_mul_f32_e32 v210, v210, v166
	v_mul_f32_e32 v211, v211, v167
	v_mul_f32_e32 v212, v212, v168
	v_mul_f32_e32 v213, v213, v169
	v_cvt_pk_bf16_f32 v206, v206, s0
	v_cvt_pk_bf16_f32 v207, v207, s0
	v_cvt_pk_bf16_f32 v208, v208, s0
	v_cvt_pk_bf16_f32 v209, v209, s0
	v_cvt_pk_bf16_f32 v210, v210, s0
	v_cvt_pk_bf16_f32 v211, v211, s0
	v_cvt_pk_bf16_f32 v212, v212, s0
	v_cvt_pk_bf16_f32 v213, v213, s0
	ds_write_b16 v160, v206 offset:0
	ds_write_b16 v160, v207 offset:256
	ds_write_b16 v160, v208 offset:512
	ds_write_b16 v160, v209 offset:768
	ds_write_b16 v161, v210 offset:0
	ds_write_b16 v161, v211 offset:256
	ds_write_b16 v161, v212 offset:512
	ds_write_b16 v161, v213 offset:768
	v_mul_f32_e32 v162, v108, v132
	v_mul_f32_e32 v163, v109, v133
	v_mul_f32_e32 v164, v110, v134
	v_mul_f32_e32 v165, v111, v135
	v_mul_f32_e32 v166, v100, v132
	v_mul_f32_e32 v167, v101, v133
	v_mul_f32_e32 v168, v102, v134
	v_mul_f32_e32 v169, v103, v135
	v_mul_f32_e32 v214, 0xbfb8aa3b, v162
	v_mul_f32_e32 v215, 0xbfb8aa3b, v163
	v_mul_f32_e32 v216, 0xbfb8aa3b, v164
	v_mul_f32_e32 v217, 0xbfb8aa3b, v165
	v_mul_f32_e32 v218, 0xbfb8aa3b, v166
	v_mul_f32_e32 v219, 0xbfb8aa3b, v167
	v_mul_f32_e32 v220, 0xbfb8aa3b, v168
	v_mul_f32_e32 v221, 0xbfb8aa3b, v169
	v_exp_f32_e32 v214, v214
	v_exp_f32_e32 v215, v215
	v_exp_f32_e32 v216, v216
	v_exp_f32_e32 v217, v217
	v_exp_f32_e32 v218, v218
	v_exp_f32_e32 v219, v219
	v_exp_f32_e32 v220, v220
	v_exp_f32_e32 v221, v221
	v_mul_f32_e32 v206, v104, v132
	v_mul_f32_e32 v207, v105, v133
	v_mul_f32_e32 v208, v106, v134
	v_mul_f32_e32 v209, v107, v135
	v_mul_f32_e32 v210, v96, v132
	v_mul_f32_e32 v211, v97, v133
	v_mul_f32_e32 v212, v98, v134
	v_mul_f32_e32 v213, v99, v135
	v_add_f32_e32 v214, 1.0, v214
	v_add_f32_e32 v215, 1.0, v215
	v_add_f32_e32 v216, 1.0, v216
	v_add_f32_e32 v217, 1.0, v217
	v_add_f32_e32 v218, 1.0, v218
	v_add_f32_e32 v219, 1.0, v219
	v_add_f32_e32 v220, 1.0, v220
	v_add_f32_e32 v221, 1.0, v221
	v_rcp_f32_e32 v214, v214
	v_rcp_f32_e32 v215, v215
	v_rcp_f32_e32 v216, v216
	v_rcp_f32_e32 v217, v217
	v_rcp_f32_e32 v218, v218
	v_rcp_f32_e32 v219, v219
	v_rcp_f32_e32 v220, v220
	v_rcp_f32_e32 v221, v221
	v_mul_f32_e32 v162, v162, v214
	v_mul_f32_e32 v163, v163, v215
	v_mul_f32_e32 v164, v164, v216
	v_mul_f32_e32 v165, v165, v217
	v_mul_f32_e32 v166, v166, v218
	v_mul_f32_e32 v167, v167, v219
	v_mul_f32_e32 v168, v168, v220
	v_mul_f32_e32 v169, v169, v221
	v_mul_f32_e32 v206, v206, v162
	v_mul_f32_e32 v207, v207, v163
	v_mul_f32_e32 v208, v208, v164
	v_mul_f32_e32 v209, v209, v165
	v_mul_f32_e32 v210, v210, v166
	v_mul_f32_e32 v211, v211, v167
	v_mul_f32_e32 v212, v212, v168
	v_mul_f32_e32 v213, v213, v169
	v_cvt_pk_bf16_f32 v206, v206, s0
	v_cvt_pk_bf16_f32 v207, v207, s0
	v_cvt_pk_bf16_f32 v208, v208, s0
	v_cvt_pk_bf16_f32 v209, v209, s0
	v_cvt_pk_bf16_f32 v210, v210, s0
	v_cvt_pk_bf16_f32 v211, v211, s0
	v_cvt_pk_bf16_f32 v212, v212, s0
	v_cvt_pk_bf16_f32 v213, v213, s0
; __device__ __forceinline__ float silu_(float x) { return x * rcp_(1.f + __expf(-x)); }
; template <int EPI>
; __device__ __forceinline__ void gemm_phase(const Params& p, const u16* __restrict__ A, const u16* __restrict__ Bt, int K, int nN,
;                            u16* __restrict__ Cout, int ldc) {
;     ...
; #pragma unroll
;       for (int m = 0; m < 8; ++m) {
; #pragma unroll
;         for (int j = 0; j < 4; ++j) {
;           const float rs = rsl[wr * 128 + m * 16 + fqe * 4 + j];
;           u16* d = stg + (wr * 128 + m * 16 + fqe * 4 + j) * 128 + (fre & 7);
; #pragma unroll
;           for (int n2 = 0; n2 < 2; ++n2) {
;             const float g = acc[m][2 * n2][j] * rs, u = acc[m][2 * n2 + 1][j] * rs;
;             const int chunk = (wc * 4 + n2 * 2 + (fre >> 3)) ^ fqe;
;             d[chunk * 8] = f2bf(silu_(g) * u);
;           }
;         }
;         __builtin_amdgcn_sched_barrier(0);
;       }
	ds_write_b16 v160, v206 offset:4096
	ds_write_b16 v160, v207 offset:4352
	ds_write_b16 v160, v208 offset:4608
	ds_write_b16 v160, v209 offset:4864
	ds_write_b16 v161, v210 offset:4096
	ds_write_b16 v161, v211 offset:4352
	ds_write_b16 v161, v212 offset:4608
	ds_write_b16 v161, v213 offset:4864
	v_mul_f32_e32 v162, v92, v136
	v_mul_f32_e32 v163, v93, v137
	v_mul_f32_e32 v164, v94, v138
	v_mul_f32_e32 v165, v95, v139
	v_mul_f32_e32 v166, v84, v136
	v_mul_f32_e32 v167, v85, v137
	v_mul_f32_e32 v168, v86, v138
	v_mul_f32_e32 v169, v87, v139
	v_mul_f32_e32 v214, 0xbfb8aa3b, v162
	v_mul_f32_e32 v215, 0xbfb8aa3b, v163
	v_mul_f32_e32 v216, 0xbfb8aa3b, v164
	v_mul_f32_e32 v217, 0xbfb8aa3b, v165
	v_mul_f32_e32 v218, 0xbfb8aa3b, v166
	v_mul_f32_e32 v219, 0xbfb8aa3b, v167
	v_mul_f32_e32 v220, 0xbfb8aa3b, v168
	v_mul_f32_e32 v221, 0xbfb8aa3b, v169
	v_exp_f32_e32 v214, v214
	v_exp_f32_e32 v215, v215
	v_exp_f32_e32 v216, v216
	v_exp_f32_e32 v217, v217
	v_exp_f32_e32 v218, v218
	v_exp_f32_e32 v219, v219
	v_exp_f32_e32 v220, v220
	v_exp_f32_e32 v221, v221
	v_mul_f32_e32 v206, v88, v136
	v_mul_f32_e32 v207, v89, v137
	v_mul_f32_e32 v208, v90, v138
	v_mul_f32_e32 v209, v91, v139
	v_mul_f32_e32 v210, v80, v136
	v_mul_f32_e32 v211, v81, v137
	v_mul_f32_e32 v212, v82, v138
	v_mul_f32_e32 v213, v83, v139
	v_add_f32_e32 v214, 1.0, v214
	v_add_f32_e32 v215, 1.0, v215
	v_add_f32_e32 v216, 1.0, v216
	v_add_f32_e32 v217, 1.0, v217
	v_add_f32_e32 v218, 1.0, v218
	v_add_f32_e32 v219, 1.0, v219
	v_add_f32_e32 v220, 1.0, v220
	v_add_f32_e32 v221, 1.0, v221
	v_rcp_f32_e32 v214, v214
	v_rcp_f32_e32 v215, v215
	v_rcp_f32_e32 v216, v216
	v_rcp_f32_e32 v217, v217
	v_rcp_f32_e32 v218, v218
	v_rcp_f32_e32 v219, v219
	v_rcp_f32_e32 v220, v220
	v_rcp_f32_e32 v221, v221
	v_mul_f32_e32 v162, v162, v214
	v_mul_f32_e32 v163, v163, v215
	v_mul_f32_e32 v164, v164, v216
	v_mul_f32_e32 v165, v165, v217
	v_mul_f32_e32 v166, v166, v218
	v_mul_f32_e32 v167, v167, v219
	v_mul_f32_e32 v168, v168, v220
	v_mul_f32_e32 v169, v169, v221
	v_mul_f32_e32 v206, v206, v162
	v_mul_f32_e32 v207, v207, v163
	v_mul_f32_e32 v208, v208, v164
	v_mul_f32_e32 v209, v209, v165
	v_mul_f32_e32 v210, v210, v166
	v_mul_f32_e32 v211, v211, v167
	v_mul_f32_e32 v212, v212, v168
	v_mul_f32_e32 v213, v213, v169
	v_cvt_pk_bf16_f32 v206, v206, s0
	v_cvt_pk_bf16_f32 v207, v207, s0
	v_cvt_pk_bf16_f32 v208, v208, s0
	v_cvt_pk_bf16_f32 v209, v209, s0
	v_cvt_pk_bf16_f32 v210, v210, s0
	v_cvt_pk_bf16_f32 v211, v211, s0
	v_cvt_pk_bf16_f32 v212, v212, s0
	v_cvt_pk_bf16_f32 v213, v213, s0
	ds_write_b16 v160, v206 offset:8192
	ds_write_b16 v160, v207 offset:8448
	ds_write_b16 v160, v208 offset:8704
	ds_write_b16 v160, v209 offset:8960
	ds_write_b16 v161, v210 offset:8192
	ds_write_b16 v161, v211 offset:8448
	ds_write_b16 v161, v212 offset:8704
	ds_write_b16 v161, v213 offset:8960
	v_mul_f32_e32 v162, v76, v140
	v_mul_f32_e32 v163, v77, v141
	v_mul_f32_e32 v164, v78, v142
	v_mul_f32_e32 v165, v79, v143
	v_mul_f32_e32 v166, v68, v140
	v_mul_f32_e32 v167, v69, v141
	v_mul_f32_e32 v168, v70, v142
	v_mul_f32_e32 v169, v71, v143
	v_mul_f32_e32 v214, 0xbfb8aa3b, v162
	v_mul_f32_e32 v215, 0xbfb8aa3b, v163
	v_mul_f32_e32 v216, 0xbfb8aa3b, v164
	v_mul_f32_e32 v217, 0xbfb8aa3b, v165
	v_mul_f32_e32 v218, 0xbfb8aa3b, v166
	v_mul_f32_e32 v219, 0xbfb8aa3b, v167
	v_mul_f32_e32 v220, 0xbfb8aa3b, v168
	v_mul_f32_e32 v221, 0xbfb8aa3b, v169
	v_exp_f32_e32 v214, v214
	v_exp_f32_e32 v215, v215
	v_exp_f32_e32 v216, v216
	v_exp_f32_e32 v217, v217
	v_exp_f32_e32 v218, v218
	v_exp_f32_e32 v219, v219
	v_exp_f32_e32 v220, v220
	v_exp_f32_e32 v221, v221
	v_mul_f32_e32 v206, v72, v140
	v_mul_f32_e32 v207, v73, v141
	v_mul_f32_e32 v208, v74, v142
	v_mul_f32_e32 v209, v75, v143
	v_mul_f32_e32 v210, v64, v140
	v_mul_f32_e32 v211, v65, v141
	v_mul_f32_e32 v212, v66, v142
	v_mul_f32_e32 v213, v67, v143
	v_add_f32_e32 v214, 1.0, v214
	v_add_f32_e32 v215, 1.0, v215
	v_add_f32_e32 v216, 1.0, v216
	v_add_f32_e32 v217, 1.0, v217
	v_add_f32_e32 v218, 1.0, v218
	v_add_f32_e32 v219, 1.0, v219
	v_add_f32_e32 v220, 1.0, v220
	v_add_f32_e32 v221, 1.0, v221
	v_rcp_f32_e32 v214, v214
	v_rcp_f32_e32 v215, v215
	v_rcp_f32_e32 v216, v216
	v_rcp_f32_e32 v217, v217
	v_rcp_f32_e32 v218, v218
	v_rcp_f32_e32 v219, v219
	v_rcp_f32_e32 v220, v220
	v_rcp_f32_e32 v221, v221
	v_mul_f32_e32 v162, v162, v214
	v_mul_f32_e32 v163, v163, v215
	v_mul_f32_e32 v164, v164, v216
	v_mul_f32_e32 v165, v165, v217
	v_mul_f32_e32 v166, v166, v218
	v_mul_f32_e32 v167, v167, v219
	v_mul_f32_e32 v168, v168, v220
	v_mul_f32_e32 v169, v169, v221
	v_mul_f32_e32 v206, v206, v162
	v_mul_f32_e32 v207, v207, v163
	v_mul_f32_e32 v208, v208, v164
	v_mul_f32_e32 v209, v209, v165
	v_mul_f32_e32 v210, v210, v166
	v_mul_f32_e32 v211, v211, v167
	v_mul_f32_e32 v212, v212, v168
	v_mul_f32_e32 v213, v213, v169
	v_cvt_pk_bf16_f32 v206, v206, s0
	v_cvt_pk_bf16_f32 v207, v207, s0
	v_cvt_pk_bf16_f32 v208, v208, s0
	v_cvt_pk_bf16_f32 v209, v209, s0
	v_cvt_pk_bf16_f32 v210, v210, s0
	v_cvt_pk_bf16_f32 v211, v211, s0
	v_cvt_pk_bf16_f32 v212, v212, s0
	v_cvt_pk_bf16_f32 v213, v213, s0
	ds_write_b16 v160, v206 offset:12288
	ds_write_b16 v160, v207 offset:12544
	ds_write_b16 v160, v208 offset:12800
	ds_write_b16 v160, v209 offset:13056
	ds_write_b16 v161, v210 offset:12288
	ds_write_b16 v161, v211 offset:12544
	ds_write_b16 v161, v212 offset:12800
	ds_write_b16 v161, v213 offset:13056
	v_mul_f32_e32 v162, v60, v144
	v_mul_f32_e32 v163, v61, v145
	v_mul_f32_e32 v164, v62, v146
	v_mul_f32_e32 v165, v63, v147
	v_mul_f32_e32 v166, v52, v144
	v_mul_f32_e32 v167, v53, v145
	v_mul_f32_e32 v168, v54, v146
	v_mul_f32_e32 v169, v55, v147
; __device__ __forceinline__ float silu_(float x) { return x * rcp_(1.f + __expf(-x)); }
; template <int EPI>
; __device__ __forceinline__ void gemm_phase(const Params& p, const u16* __restrict__ A, const u16* __restrict__ Bt, int K, int nN,
;                            u16* __restrict__ Cout, int ldc) {
;     ...
; #pragma unroll
;       for (int m = 0; m < 8; ++m) {
; #pragma unroll
;         for (int j = 0; j < 4; ++j) {
;           const float rs = rsl[wr * 128 + m * 16 + fqe * 4 + j];
;           u16* d = stg + (wr * 128 + m * 16 + fqe * 4 + j) * 128 + (fre & 7);
; #pragma unroll
;           for (int n2 = 0; n2 < 2; ++n2) {
;             const float g = acc[m][2 * n2][j] * rs, u = acc[m][2 * n2 + 1][j] * rs;
;             const int chunk = (wc * 4 + n2 * 2 + (fre >> 3)) ^ fqe;
;             d[chunk * 8] = f2bf(silu_(g) * u);
;           }
;         }
;         __builtin_amdgcn_sched_barrier(0);
;       }
	v_mul_f32_e32 v214, 0xbfb8aa3b, v162
	v_mul_f32_e32 v215, 0xbfb8aa3b, v163
	v_mul_f32_e32 v216, 0xbfb8aa3b, v164
	v_mul_f32_e32 v217, 0xbfb8aa3b, v165
	v_mul_f32_e32 v218, 0xbfb8aa3b, v166
	v_mul_f32_e32 v219, 0xbfb8aa3b, v167
	v_mul_f32_e32 v220, 0xbfb8aa3b, v168
	v_mul_f32_e32 v221, 0xbfb8aa3b, v169
	v_exp_f32_e32 v214, v214
	v_exp_f32_e32 v215, v215
	v_exp_f32_e32 v216, v216
	v_exp_f32_e32 v217, v217
	v_exp_f32_e32 v218, v218
	v_exp_f32_e32 v219, v219
	v_exp_f32_e32 v220, v220
	v_exp_f32_e32 v221, v221
	v_mul_f32_e32 v206, v56, v144
	v_mul_f32_e32 v207, v57, v145
	v_mul_f32_e32 v208, v58, v146
	v_mul_f32_e32 v209, v59, v147
	v_mul_f32_e32 v210, v48, v144
	v_mul_f32_e32 v211, v49, v145
	v_mul_f32_e32 v212, v50, v146
	v_mul_f32_e32 v213, v51, v147
	v_add_f32_e32 v214, 1.0, v214
	v_add_f32_e32 v215, 1.0, v215
	v_add_f32_e32 v216, 1.0, v216
	v_add_f32_e32 v217, 1.0, v217
	v_add_f32_e32 v218, 1.0, v218
	v_add_f32_e32 v219, 1.0, v219
	v_add_f32_e32 v220, 1.0, v220
	v_add_f32_e32 v221, 1.0, v221
	v_rcp_f32_e32 v214, v214
	v_rcp_f32_e32 v215, v215
	v_rcp_f32_e32 v216, v216
	v_rcp_f32_e32 v217, v217
	v_rcp_f32_e32 v218, v218
	v_rcp_f32_e32 v219, v219
	v_rcp_f32_e32 v220, v220
	v_rcp_f32_e32 v221, v221
	v_mul_f32_e32 v162, v162, v214
	v_mul_f32_e32 v163, v163, v215
	v_mul_f32_e32 v164, v164, v216
	v_mul_f32_e32 v165, v165, v217
	v_mul_f32_e32 v166, v166, v218
	v_mul_f32_e32 v167, v167, v219
	v_mul_f32_e32 v168, v168, v220
	v_mul_f32_e32 v169, v169, v221
	v_mul_f32_e32 v206, v206, v162
	v_mul_f32_e32 v207, v207, v163
	v_mul_f32_e32 v208, v208, v164
	v_mul_f32_e32 v209, v209, v165
	v_mul_f32_e32 v210, v210, v166
	v_mul_f32_e32 v211, v211, v167
	v_mul_f32_e32 v212, v212, v168
	v_mul_f32_e32 v213, v213, v169
	v_cvt_pk_bf16_f32 v206, v206, s0
	v_cvt_pk_bf16_f32 v207, v207, s0
	v_cvt_pk_bf16_f32 v208, v208, s0
	v_cvt_pk_bf16_f32 v209, v209, s0
	v_cvt_pk_bf16_f32 v210, v210, s0
	v_cvt_pk_bf16_f32 v211, v211, s0
	v_cvt_pk_bf16_f32 v212, v212, s0
	v_cvt_pk_bf16_f32 v213, v213, s0
	ds_write_b16 v160, v206 offset:16384
	ds_write_b16 v160, v207 offset:16640
	ds_write_b16 v160, v208 offset:16896
	ds_write_b16 v160, v209 offset:17152
	ds_write_b16 v161, v210 offset:16384
	ds_write_b16 v161, v211 offset:16640
	ds_write_b16 v161, v212 offset:16896
	ds_write_b16 v161, v213 offset:17152
	v_mul_f32_e32 v162, v44, v148
	v_mul_f32_e32 v163, v45, v149
	v_mul_f32_e32 v164, v46, v150
	v_mul_f32_e32 v165, v47, v151
	v_mul_f32_e32 v166, v36, v148
	v_mul_f32_e32 v167, v37, v149
	v_mul_f32_e32 v168, v38, v150
	v_mul_f32_e32 v169, v39, v151
	v_mul_f32_e32 v214, 0xbfb8aa3b, v162
	v_mul_f32_e32 v215, 0xbfb8aa3b, v163
	v_mul_f32_e32 v216, 0xbfb8aa3b, v164
	v_mul_f32_e32 v217, 0xbfb8aa3b, v165
	v_mul_f32_e32 v218, 0xbfb8aa3b, v166
	v_mul_f32_e32 v219, 0xbfb8aa3b, v167
	v_mul_f32_e32 v220, 0xbfb8aa3b, v168
	v_mul_f32_e32 v221, 0xbfb8aa3b, v169
	v_exp_f32_e32 v214, v214
	v_exp_f32_e32 v215, v215
	v_exp_f32_e32 v216, v216
	v_exp_f32_e32 v217, v217
	v_exp_f32_e32 v218, v218
	v_exp_f32_e32 v219, v219
	v_exp_f32_e32 v220, v220
	v_exp_f32_e32 v221, v221
	v_mul_f32_e32 v206, v40, v148
	v_mul_f32_e32 v207, v41, v149
	v_mul_f32_e32 v208, v42, v150
	v_mul_f32_e32 v209, v43, v151
	v_mul_f32_e32 v210, v32, v148
	v_mul_f32_e32 v211, v33, v149
	v_mul_f32_e32 v212, v34, v150
	v_mul_f32_e32 v213, v35, v151
	v_add_f32_e32 v214, 1.0, v214
	v_add_f32_e32 v215, 1.0, v215
	v_add_f32_e32 v216, 1.0, v216
	v_add_f32_e32 v217, 1.0, v217
	v_add_f32_e32 v218, 1.0, v218
	v_add_f32_e32 v219, 1.0, v219
	v_add_f32_e32 v220, 1.0, v220
	v_add_f32_e32 v221, 1.0, v221
	v_rcp_f32_e32 v214, v214
	v_rcp_f32_e32 v215, v215
	v_rcp_f32_e32 v216, v216
	v_rcp_f32_e32 v217, v217
	v_rcp_f32_e32 v218, v218
	v_rcp_f32_e32 v219, v219
	v_rcp_f32_e32 v220, v220
	v_rcp_f32_e32 v221, v221
	v_mul_f32_e32 v162, v162, v214
	v_mul_f32_e32 v163, v163, v215
	v_mul_f32_e32 v164, v164, v216
	v_mul_f32_e32 v165, v165, v217
	v_mul_f32_e32 v166, v166, v218
	v_mul_f32_e32 v167, v167, v219
	v_mul_f32_e32 v168, v168, v220
	v_mul_f32_e32 v169, v169, v221
	v_mul_f32_e32 v206, v206, v162
	v_mul_f32_e32 v207, v207, v163
	v_mul_f32_e32 v208, v208, v164
	v_mul_f32_e32 v209, v209, v165
	v_mul_f32_e32 v210, v210, v166
	v_mul_f32_e32 v211, v211, v167
	v_mul_f32_e32 v212, v212, v168
	v_mul_f32_e32 v213, v213, v169
	v_cvt_pk_bf16_f32 v206, v206, s0
	v_cvt_pk_bf16_f32 v207, v207, s0
	v_cvt_pk_bf16_f32 v208, v208, s0
	v_cvt_pk_bf16_f32 v209, v209, s0
	v_cvt_pk_bf16_f32 v210, v210, s0
	v_cvt_pk_bf16_f32 v211, v211, s0
	v_cvt_pk_bf16_f32 v212, v212, s0
	v_cvt_pk_bf16_f32 v213, v213, s0
	ds_write_b16 v160, v206 offset:20480
	ds_write_b16 v160, v207 offset:20736
	ds_write_b16 v160, v208 offset:20992
	ds_write_b16 v160, v209 offset:21248
	ds_write_b16 v161, v210 offset:20480
	ds_write_b16 v161, v211 offset:20736
	ds_write_b16 v161, v212 offset:20992
	ds_write_b16 v161, v213 offset:21248
	v_mul_f32_e32 v162, v28, v152
	v_mul_f32_e32 v163, v29, v153
	v_mul_f32_e32 v164, v30, v154
	v_mul_f32_e32 v165, v31, v155
	v_mul_f32_e32 v166, v20, v152
	v_mul_f32_e32 v167, v21, v153
	v_mul_f32_e32 v168, v22, v154
	v_mul_f32_e32 v169, v23, v155
	v_mul_f32_e32 v214, 0xbfb8aa3b, v162
	v_mul_f32_e32 v215, 0xbfb8aa3b, v163
	v_mul_f32_e32 v216, 0xbfb8aa3b, v164
	v_mul_f32_e32 v217, 0xbfb8aa3b, v165
	v_mul_f32_e32 v218, 0xbfb8aa3b, v166
	v_mul_f32_e32 v219, 0xbfb8aa3b, v167
	v_mul_f32_e32 v220, 0xbfb8aa3b, v168
	v_mul_f32_e32 v221, 0xbfb8aa3b, v169
	v_exp_f32_e32 v214, v214
	v_exp_f32_e32 v215, v215
	v_exp_f32_e32 v216, v216
	v_exp_f32_e32 v217, v217
	v_exp_f32_e32 v218, v218
	v_exp_f32_e32 v219, v219
	v_exp_f32_e32 v220, v220
	v_exp_f32_e32 v221, v221
	v_mul_f32_e32 v206, v24, v152
; __device__ __forceinline__ float silu_(float x) { return x * rcp_(1.f + __expf(-x)); }
; template <int EPI>
; __device__ __forceinline__ void gemm_phase(const Params& p, const u16* __restrict__ A, const u16* __restrict__ Bt, int K, int nN,
;                            u16* __restrict__ Cout, int ldc) {
;     ...
; #pragma unroll
;       for (int m = 0; m < 8; ++m) {
; #pragma unroll
;         for (int j = 0; j < 4; ++j) {
;           const float rs = rsl[wr * 128 + m * 16 + fqe * 4 + j];
;           u16* d = stg + (wr * 128 + m * 16 + fqe * 4 + j) * 128 + (fre & 7);
; #pragma unroll
;           for (int n2 = 0; n2 < 2; ++n2) {
;             const float g = acc[m][2 * n2][j] * rs, u = acc[m][2 * n2 + 1][j] * rs;
;             const int chunk = (wc * 4 + n2 * 2 + (fre >> 3)) ^ fqe;
;             d[chunk * 8] = f2bf(silu_(g) * u);
;           }
;         }
;         __builtin_amdgcn_sched_barrier(0);
;       }
;       __syncthreads();
; #pragma unroll
;       for (int it = 0; it < 8; ++it) {
;         const int id = it * 512 + tide, r = id >> 4, ck = id & 15;
;         const uint4 v = *(const uint4*)(stg + r * 128 + ((ck ^ ((r >> 2) & 3)) * 8));
	v_mul_f32_e32 v207, v25, v153
	v_mul_f32_e32 v208, v26, v154
	v_mul_f32_e32 v209, v27, v155
	v_mul_f32_e32 v210, v16, v152
	v_mul_f32_e32 v211, v17, v153
	v_mul_f32_e32 v212, v18, v154
	v_mul_f32_e32 v213, v19, v155
	v_add_f32_e32 v214, 1.0, v214
	v_add_f32_e32 v215, 1.0, v215
	v_add_f32_e32 v216, 1.0, v216
	v_add_f32_e32 v217, 1.0, v217
	v_add_f32_e32 v218, 1.0, v218
	v_add_f32_e32 v219, 1.0, v219
	v_add_f32_e32 v220, 1.0, v220
	v_add_f32_e32 v221, 1.0, v221
	v_rcp_f32_e32 v214, v214
	v_rcp_f32_e32 v215, v215
	v_rcp_f32_e32 v216, v216
	v_rcp_f32_e32 v217, v217
	v_rcp_f32_e32 v218, v218
	v_rcp_f32_e32 v219, v219
	v_rcp_f32_e32 v220, v220
	v_rcp_f32_e32 v221, v221
	v_mul_f32_e32 v162, v162, v214
	v_mul_f32_e32 v163, v163, v215
	v_mul_f32_e32 v164, v164, v216
	v_mul_f32_e32 v165, v165, v217
	v_mul_f32_e32 v166, v166, v218
	v_mul_f32_e32 v167, v167, v219
	v_mul_f32_e32 v168, v168, v220
	v_mul_f32_e32 v169, v169, v221
	v_mul_f32_e32 v206, v206, v162
	v_mul_f32_e32 v207, v207, v163
	v_mul_f32_e32 v208, v208, v164
	v_mul_f32_e32 v209, v209, v165
	v_mul_f32_e32 v210, v210, v166
	v_mul_f32_e32 v211, v211, v167
	v_mul_f32_e32 v212, v212, v168
	v_mul_f32_e32 v213, v213, v169
	v_cvt_pk_bf16_f32 v206, v206, s0
	v_cvt_pk_bf16_f32 v207, v207, s0
	v_cvt_pk_bf16_f32 v208, v208, s0
	v_cvt_pk_bf16_f32 v209, v209, s0
	v_cvt_pk_bf16_f32 v210, v210, s0
	v_cvt_pk_bf16_f32 v211, v211, s0
	v_cvt_pk_bf16_f32 v212, v212, s0
	v_cvt_pk_bf16_f32 v213, v213, s0
	ds_write_b16 v160, v206 offset:24576
	ds_write_b16 v160, v207 offset:24832
	ds_write_b16 v160, v208 offset:25088
	ds_write_b16 v160, v209 offset:25344
	ds_write_b16 v161, v210 offset:24576
	ds_write_b16 v161, v211 offset:24832
	ds_write_b16 v161, v212 offset:25088
	ds_write_b16 v161, v213 offset:25344
	v_mul_f32_e32 v162, v12, v156
	v_mul_f32_e32 v163, v13, v157
	v_mul_f32_e32 v164, v14, v158
	v_mul_f32_e32 v165, v15, v159
	v_mul_f32_e32 v166, v4, v156
	v_mul_f32_e32 v167, v5, v157
	v_mul_f32_e32 v168, v6, v158
	v_mul_f32_e32 v169, v7, v159
	v_mul_f32_e32 v214, 0xbfb8aa3b, v162
	v_mul_f32_e32 v215, 0xbfb8aa3b, v163
	v_mul_f32_e32 v216, 0xbfb8aa3b, v164
	v_mul_f32_e32 v217, 0xbfb8aa3b, v165
	v_mul_f32_e32 v218, 0xbfb8aa3b, v166
	v_mul_f32_e32 v219, 0xbfb8aa3b, v167
	v_mul_f32_e32 v220, 0xbfb8aa3b, v168
	v_mul_f32_e32 v221, 0xbfb8aa3b, v169
	v_exp_f32_e32 v214, v214
	v_exp_f32_e32 v215, v215
	v_exp_f32_e32 v216, v216
	v_exp_f32_e32 v217, v217
	v_exp_f32_e32 v218, v218
	v_exp_f32_e32 v219, v219
	v_exp_f32_e32 v220, v220
	v_exp_f32_e32 v221, v221
	v_mul_f32_e32 v206, v8, v156
	v_mul_f32_e32 v207, v9, v157
	v_mul_f32_e32 v208, v10, v158
	v_mul_f32_e32 v209, v11, v159
	v_mul_f32_e32 v210, v0, v156
	v_mul_f32_e32 v211, v1, v157
	v_mul_f32_e32 v212, v2, v158
	v_mul_f32_e32 v213, v3, v159
	v_add_f32_e32 v214, 1.0, v214
	v_add_f32_e32 v215, 1.0, v215
	v_add_f32_e32 v216, 1.0, v216
	v_add_f32_e32 v217, 1.0, v217
	v_add_f32_e32 v218, 1.0, v218
	v_add_f32_e32 v219, 1.0, v219
	v_add_f32_e32 v220, 1.0, v220
	v_add_f32_e32 v221, 1.0, v221
	v_rcp_f32_e32 v214, v214
	v_rcp_f32_e32 v215, v215
	v_rcp_f32_e32 v216, v216
	v_rcp_f32_e32 v217, v217
	v_rcp_f32_e32 v218, v218
	v_rcp_f32_e32 v219, v219
	v_rcp_f32_e32 v220, v220
	v_rcp_f32_e32 v221, v221
	v_mul_f32_e32 v162, v162, v214
	v_mul_f32_e32 v163, v163, v215
	v_mul_f32_e32 v164, v164, v216
	v_mul_f32_e32 v165, v165, v217
	v_mul_f32_e32 v166, v166, v218
	v_mul_f32_e32 v167, v167, v219
	v_mul_f32_e32 v168, v168, v220
	v_mul_f32_e32 v169, v169, v221
	v_mul_f32_e32 v206, v206, v162
	v_mul_f32_e32 v207, v207, v163
	v_mul_f32_e32 v208, v208, v164
	v_mul_f32_e32 v209, v209, v165
	v_mul_f32_e32 v210, v210, v166
	v_mul_f32_e32 v211, v211, v167
	v_mul_f32_e32 v212, v212, v168
	v_mul_f32_e32 v213, v213, v169
	v_cvt_pk_bf16_f32 v206, v206, s0
	v_cvt_pk_bf16_f32 v207, v207, s0
	v_cvt_pk_bf16_f32 v208, v208, s0
	v_cvt_pk_bf16_f32 v209, v209, s0
	v_cvt_pk_bf16_f32 v210, v210, s0
	v_cvt_pk_bf16_f32 v211, v211, s0
	v_cvt_pk_bf16_f32 v212, v212, s0
	v_cvt_pk_bf16_f32 v213, v213, s0
	ds_write_b16 v160, v206 offset:28672
	ds_write_b16 v160, v207 offset:28928
	ds_write_b16 v160, v208 offset:29184
	ds_write_b16 v160, v209 offset:29440
	ds_write_b16 v161, v210 offset:28672
	ds_write_b16 v161, v211 offset:28928
	ds_write_b16 v161, v212 offset:29184
	ds_write_b16 v161, v213 offset:29440
	v_mov_b32_e32 v128, v173
	v_and_b32_e32 v0, 15, v128
	v_lshrrev_b32_e32 v1, 6, v128
	v_bitop3_b32 v1, v1, v0, 3 bitop3:0x6c
	s_lshl_b32 s2, s39, 7
	v_lshl_or_b32 v8, v1, 4, v188
	v_lshl_or_b32 v0, v0, 3, s2
	v_mov_b32_e32 v1, v172
	v_ashrrev_i32_e32 v6, 4, v128
	v_lshl_add_u64 v[4:5], v[0:1], 1, s[4:5]
	v_lshl_add_u32 v0, v6, 8, v8
	s_waitcnt lgkmcnt(0)
	s_barrier
; template <int EPI>
; __device__ __forceinline__ void gemm_phase(const Params& p, const u16* __restrict__ A, const u16* __restrict__ Bt, int K, int nN,
;                            u16* __restrict__ Cout, int ldc) {
;     ...
; #pragma unroll
;       for (int it = 0; it < 8; ++it) {
;         const int id = it * 512 + tide, r = id >> 4, ck = id & 15;
;         const uint4 v = *(const uint4*)(stg + r * 128 + ((ck ^ ((r >> 2) & 3)) * 8));
;         { typedef __attribute__((ext_vector_type(4))) unsigned u32x4_; const u32x4_ t_ = {v.x, v.y, v.z, v.w};
;           __builtin_nontemporal_store(t_, (u32x4_*)(Cout + (unsigned)(brow + r) * (unsigned)ldc + (unsigned)((bcol >> 1) + ck * 8))); }
;       }
;       asm volatile("s_waitcnt lgkmcnt(0)" ::: "memory"); __builtin_amdgcn_s_barrier();
	ds_read_b128 v[0:3], v0
	v_add_u32_e32 v6, s12, v6
	v_mul_lo_u32 v6, v6, s58
	v_mov_b32_e32 v7, v172
	v_lshl_add_u64 v[6:7], v[6:7], 1, v[4:5]
	s_waitcnt lgkmcnt(0)
	flat_store_dwordx4 v[6:7], v[0:3] nt
	v_mov_b32_e32 v7, v172
	s_mov_b64 s[26:27], -1
	v_add_u32_e32 v0, 0x200, v128
	v_ashrrev_i32_e32 v6, 4, v0
	v_lshl_add_u32 v0, v6, 8, v8
	ds_read_b128 v[0:3], v0
	v_add_u32_e32 v6, s12, v6
	v_mul_lo_u32 v6, v6, s58
	v_lshl_add_u64 v[6:7], v[6:7], 1, v[4:5]
	s_and_b64 vcc, exec, s[14:15]
	s_waitcnt lgkmcnt(0)
	flat_store_dwordx4 v[6:7], v[0:3] nt
	v_mov_b32_e32 v7, v172
	s_nop 0
	v_add_u32_e32 v0, 0x400, v128
	v_ashrrev_i32_e32 v6, 4, v0
	v_lshl_add_u32 v0, v6, 8, v8
	ds_read_b128 v[0:3], v0
	v_add_u32_e32 v6, s12, v6
	v_mul_lo_u32 v6, v6, s58
	v_lshl_add_u64 v[6:7], v[6:7], 1, v[4:5]
	s_waitcnt lgkmcnt(0)
	flat_store_dwordx4 v[6:7], v[0:3] nt
	v_mov_b32_e32 v7, v172
	s_nop 0
	v_add_u32_e32 v0, 0x600, v128
	v_ashrrev_i32_e32 v6, 4, v0
	v_lshl_add_u32 v0, v6, 8, v8
	ds_read_b128 v[0:3], v0
	v_add_u32_e32 v6, s12, v6
	v_mul_lo_u32 v6, v6, s58
	v_lshl_add_u64 v[6:7], v[6:7], 1, v[4:5]
	s_waitcnt lgkmcnt(0)
	flat_store_dwordx4 v[6:7], v[0:3] nt
	v_mov_b32_e32 v7, v172
	s_nop 0
	v_add_u32_e32 v0, 0x800, v128
	v_ashrrev_i32_e32 v6, 4, v0
	v_lshl_add_u32 v0, v6, 8, v8
	ds_read_b128 v[0:3], v0
	v_add_u32_e32 v6, s12, v6
	v_mul_lo_u32 v6, v6, s58
	v_lshl_add_u64 v[6:7], v[6:7], 1, v[4:5]
	s_waitcnt lgkmcnt(0)
	flat_store_dwordx4 v[6:7], v[0:3] nt
	v_mov_b32_e32 v7, v172
	s_nop 0
	v_add_u32_e32 v0, 0xa00, v128
	v_ashrrev_i32_e32 v6, 4, v0
	v_lshl_add_u32 v0, v6, 8, v8
	ds_read_b128 v[0:3], v0
	v_add_u32_e32 v6, s12, v6
	v_mul_lo_u32 v6, v6, s58
	v_lshl_add_u64 v[6:7], v[6:7], 1, v[4:5]
	s_waitcnt lgkmcnt(0)
	flat_store_dwordx4 v[6:7], v[0:3] nt
	v_mov_b32_e32 v7, v172
	s_nop 0
	v_add_u32_e32 v0, 0xc00, v128
	v_ashrrev_i32_e32 v6, 4, v0
	v_lshl_add_u32 v0, v6, 8, v8
	ds_read_b128 v[0:3], v0
	v_add_u32_e32 v6, s12, v6
	v_mul_lo_u32 v6, v6, s58
	v_lshl_add_u64 v[6:7], v[6:7], 1, v[4:5]
	s_waitcnt lgkmcnt(0)
	flat_store_dwordx4 v[6:7], v[0:3] nt
	v_mov_b32_e32 v7, v172
	s_nop 0
	v_add_u32_e32 v0, 0xe00, v128
	v_ashrrev_i32_e32 v6, 4, v0
	v_lshl_add_u32 v0, v6, 8, v8
	ds_read_b128 v[0:3], v0
	v_add_u32_e32 v6, s12, v6
	v_mul_lo_u32 v6, v6, s58
	v_lshl_add_u64 v[4:5], v[6:7], 1, v[4:5]
	s_waitcnt lgkmcnt(0)
	flat_store_dwordx4 v[4:5], v[0:3] nt
	s_waitcnt lgkmcnt(0)
	s_barrier
	s_cbranch_vccnz .LBB0_1153
